# diff-attn loop common-path trims (rare rescale path out of line behind one scalar test, canonicalising max pairs collapsed, running sum kept in place) on top of SGPR-base LDS-DMA addressing in the dif
# speedup vs baseline: 1.0139x; 1.0048x over previous
; #define SBAR() __builtin_amdgcn_sched_barrier(0)
; __device__ __forceinline__ int v_rd_base(int lane) { return ((lane & 3) << 3) | (((lane >> 2) & 3) << 6) | (((lane >> 4) & 1) << 5) | (((lane >> 5) & 1) << 8); }
; #define A3_BAR() do { asm volatile("s_waitcnt vmcnt(0) lgkmcnt(0)" ::: "memory"); __builtin_amdgcn_s_barrier(); asm volatile("" ::: "memory"); } while (0)
; #define lane lane_id()
; template <int KB, bool SK>
; __device__ __forceinline__ void qkt(f32x16& p0, f32x16& p1, const char* K_lds, int r32, int hi, const bf16x8* qr, bool act) {
;     if (SK && !act) return;
;     p0 = f32x16{}; p1 = f32x16{};
;     const char* kb[4];
; #pragma unroll
;     for (int dd = 0; dd < 4; ++dd) kb[dd] = K_lds + KB * SHM_K + KSWZ(r32, (dd * 16 + hi * 8) * 2);
; #pragma unroll
;     for (int d0 = 0; d0 < 8; ++d0) { const char* a = kb[d0 & 3] + (d0 >> 2) * 128;
;         bf16x8 b0 = *reinterpret_cast<const bf16x8*>(a);
;         bf16x8 b1 = *reinterpret_cast<const bf16x8*>(a + 32 * 256);
;         p0 = __builtin_amdgcn_mfma_f32_32x32x16_bf16(b0, qr[d0], p0, 0, 0, 0);
;         p1 = __builtin_amdgcn_mfma_f32_32x32x16_bf16(b1, qr[d0], p1, 0, 0, 0); }
; }
; __device__ __forceinline__ void attn_block3(const BlockRef& cur, char* lds, const int wid) {
;     ...
;     A3_DMA(0);
;     A3_BAR();
;     float m_reg = -1e30f, l_reg = 0; f32x16 o[4] = {}, o2[4] = {};
;     const int vbase = (int)(uintptr_t)V_lds + v_rd_base(lane);
;     for (int t = 0; t < NT; ++t) {
;         f32x16 p0, p1; float mn, alpha; bf16x8 pa0, pa1, pa2, pa3;
;         const int kb = t * KVBLK;
;         qkt<0, false>(p0, p1, K_lds + (t & 1) * SHM_K, r32, hi, qr, true);
;         SBAR(); if (t + 1 < NT) A3_DMA(t + 1);
.LBB0_449:
	s_and_b32 s95, s93, 1
	s_lshl_b32 s7, s95, 14
	s_add_i32 s7, s7, 0x10000
	v_add3_u32 v0, s7, v242, v240
	ds_read_b128 v[2:5], v0
	ds_read_b128 v[10:13], v0 offset:8192
	v_add3_u32 v6, s7, v243, v240
	ds_read_b128 v[176:179], v6
	ds_read_b128 v[180:183], v6 offset:8192
	v_add3_u32 v7, s7, v244, v240
	ds_read_b128 v[184:187], v7
	ds_read_b128 v[188:191], v7 offset:8192
	s_mov_b32 s6, s93
	s_waitcnt lgkmcnt(5)
	v_mfma_f32_32x32x16_bf16 v[160:175], v[2:5], v[192:195], 0
	v_add3_u32 v8, s7, v245, v240
	ds_read_b128 v[2:5], v8
	s_waitcnt lgkmcnt(5)
	v_mfma_f32_32x32x16_bf16 v[144:159], v[10:13], v[192:195], 0
	ds_read_b128 v[10:13], v8 offset:8192
	s_waitcnt lgkmcnt(5)
	v_mfma_f32_32x32x16_bf16 v[160:175], v[176:179], v[196:199], v[160:175]
	ds_read_b128 v[176:179], v0 offset:128
	s_waitcnt lgkmcnt(5)
	v_mfma_f32_32x32x16_bf16 v[144:159], v[180:183], v[196:199], v[144:159]
	ds_read_b128 v[180:183], v0 offset:8320
	s_waitcnt lgkmcnt(5)
	v_mfma_f32_32x32x16_bf16 v[160:175], v[184:187], v[200:203], v[160:175]
	ds_read_b128 v[184:187], v6 offset:128
	s_waitcnt lgkmcnt(5)
	v_mfma_f32_32x32x16_bf16 v[144:159], v[188:191], v[200:203], v[144:159]
	ds_read_b128 v[188:191], v6 offset:8320
	s_waitcnt lgkmcnt(5)
	v_mfma_f32_32x32x16_bf16 v[160:175], v[2:5], v[204:207], v[160:175]
	ds_read_b128 v[2:5], v7 offset:128
	s_waitcnt lgkmcnt(5)
	v_mfma_f32_32x32x16_bf16 v[144:159], v[10:13], v[204:207], v[144:159]
	ds_read_b128 v[10:13], v7 offset:8320
	s_waitcnt lgkmcnt(5)
	v_mfma_f32_32x32x16_bf16 v[160:175], v[176:179], v[208:211], v[160:175]
	ds_read_b128 v[176:179], v8 offset:128
	s_waitcnt lgkmcnt(5)
	v_mfma_f32_32x32x16_bf16 v[144:159], v[180:183], v[208:211], v[144:159]
	ds_read_b128 v[180:183], v8 offset:8320
	s_waitcnt lgkmcnt(5)
	v_mfma_f32_32x32x16_bf16 v[160:175], v[184:187], v[212:215], v[160:175]
	s_waitcnt lgkmcnt(4)
	v_mfma_f32_32x32x16_bf16 v[144:159], v[188:191], v[212:215], v[144:159]
	s_waitcnt lgkmcnt(3)
	v_mfma_f32_32x32x16_bf16 v[160:175], v[2:5], v[216:219], v[160:175]
	s_waitcnt lgkmcnt(2)
	v_mfma_f32_32x32x16_bf16 v[144:159], v[10:13], v[216:219], v[144:159]
	s_waitcnt lgkmcnt(1)
	v_mfma_f32_32x32x16_bf16 v[160:175], v[176:179], v[220:223], v[160:175]
	s_waitcnt lgkmcnt(0)
	v_mfma_f32_32x32x16_bf16 v[144:159], v[180:183], v[220:223], v[144:159]
	s_add_i32 s93, s93, 1
	s_cmp_ge_u32 s6, s87
	s_cbranch_scc1 .LBB0_451
	s_and_b32 s6, s93, 1
	s_lshl_b32 s7, s6, 14
	s_add_i32 s7, s83, s7
	s_lshl_b32 s6, s6, 15
	s_mov_b32 m0, s7
	s_add_i32 s6, s82, s6
	global_load_lds_dwordx4 v228, s[68:69]
	s_mov_b32 m0, s6
	s_add_i32 s20, s6, 0x4000
	global_load_lds_dwordx4 v224, s[98:99]
	s_mov_b32 m0, s20
	s_nop 0
	global_load_lds_dwordx4 v224, s[100:101]
	s_add_i32 m0, s7, 0x400
	s_nop 0
	global_load_lds_dwordx4 v230, s[68:69]
	s_add_i32 m0, s6, 0x400
	s_nop 0
	global_load_lds_dwordx4 v225, s[98:99]
	s_add_i32 m0, s6, 0x4400
	s_nop 0
	global_load_lds_dwordx4 v225, s[100:101]
